# grid barrier: non-leader workgroups issue their L1 invalidate before spinning on the release word (no loads happen in between) instead of after
# speedup vs baseline: 1.0115x; 1.0115x over previous
.LBB0_1610:
	s_or_b64 exec, exec, s[10:11]
	v_cvt_f32_u32_e32 v5, v3
	s_waitcnt vmcnt(0)
	v_readfirstlane_b32 s8, v4
	v_sub_u32_e32 v4, 0, v3
	v_rcp_iflag_f32_e32 v5, v5
	v_add_u32_e32 v6, s8, v2
	v_mul_f32_e32 v5, 0x4f7ffffe, v5
	v_cvt_u32_f32_e32 v5, v5
	v_mul_lo_u32 v2, v4, v5
	v_mul_hi_u32 v2, v5, v2
	v_add_u32_e32 v2, v5, v2
	v_mul_hi_u32 v2, v6, v2
	v_mul_lo_u32 v4, v2, v3
	v_sub_u32_e32 v4, v6, v4
	v_add_u32_e32 v5, 1, v2
	v_cmp_ge_u32_e32 vcc, v4, v3
	s_nop 1
	v_cndmask_b32_e32 v2, v2, v5, vcc
	v_sub_u32_e32 v5, v4, v3
	v_cndmask_b32_e32 v4, v4, v5, vcc
	v_add_u32_e32 v5, 1, v2
	v_cmp_ge_u32_e32 vcc, v4, v3
	v_add_u32_e32 v4, 1, v6
	s_nop 0
	v_cndmask_b32_e32 v2, v2, v5, vcc
	v_mul_lo_u32 v5, v3, v2
	v_add_u32_e32 v3, v5, v3
	v_cmp_ne_u32_e32 vcc, v4, v3
	s_and_saveexec_b64 s[8:9], vcc
	s_xor_b64 s[8:9], exec, s[8:9]
	s_cbranch_execz .LBB0_1624
	s_waitcnt lgkmcnt(0)
	buffer_inv sc1
	v_mov_b32_e32 v0, 0x2000
	global_load_dword v0, v0, s[6:7] offset:1024 sc1
	s_add_u32 s14, s6, 0x2400
	s_addc_u32 s15, s7, 0
	s_waitcnt vmcnt(0)
	v_cmp_eq_u32_e32 vcc, v0, v2
	s_and_saveexec_b64 s[10:11], vcc
	s_cbranch_execz .LBB0_1623
	s_add_u32 s12, s46, 0x100200
	s_addc_u32 s13, s47, 0
	s_mov_b32 s26, 1
	s_mov_b64 s[16:17], 0
	s_branch .LBB0_1614

.LBB0_1623:
	s_or_b64 exec, exec, s[10:11]
	s_waitcnt vmcnt(0)
	s_waitcnt vmcnt(0)
